# speedup vs baseline: 1.0135x; 1.0135x over previous
.LBB0_622:
	v_bitop3_b32 v13, v213, v13, 2 bitop3:0x36
	v_lshlrev_b32_e32 v180, 4, v13
	s_andn2_b64 vcc, exec, s[16:17]
	v_mov_b32_e32 v115, 0
	s_cbranch_vccnz .LBB0_625
	s_add_i32 s1, s5, -1
	s_add_u32 s35, s35, 0x80
	v_lshl_add_u64 v[168:169], s[14:15], 0, v[6:7]
	s_addc_u32 s19, s19, 0
	s_lshl_b64 s[14:15], s[46:47], 9
	s_or_b32 s16, s14, 48
	s_mul_i32 s17, s16, s13
	s_mul_hi_u32 s39, s16, s12
	s_add_i32 s17, s39, s17
	s_mul_i32 s15, s15, s12
	v_lshl_add_u64 v[166:167], v[8:9], 0, v[6:7]
	s_add_i32 s17, s17, s15
	s_mul_i32 s16, s16, s12
	v_add_u32_e32 v6, s33, v11
	v_mul_lo_u32 v8, s38, v6
	s_add_u32 s16, s35, s16
	v_add_u32_e32 v6, v8, v12
	v_mov_b32_e32 v7, v2
	s_addc_u32 s17, s19, s17
	v_lshl_add_u64 v[170:171], s[16:17], 0, v[6:7]
	s_lshl_b64 s[16:17], s[2:3], 9
	s_or_b32 s3, s16, 48
	s_mul_i32 s17, s17, s12
	s_mul_i32 s33, s3, s13
	v_mov_b32_e32 v9, s12
	s_add_i32 s33, s33, s17
	v_mad_u64_u32 v[6:7], s[38:39], s3, v9, v[6:7]
	v_lshl_add_u64 v[4:5], v[4:5], 0, s[66:67]
	v_add_u32_e32 v7, s33, v7
	s_or_b32 s3, s16, 32
	v_lshl_add_u64 v[172:173], v[4:5], 0, v[6:7]
	v_add_u32_e32 v6, v8, v10
	v_mov_b32_e32 v7, v2
	s_mul_i32 s16, s3, s13
	s_add_i32 s33, s16, s17
	v_mad_u64_u32 v[8:9], s[16:17], s3, v9, v[6:7]
	s_or_b32 s3, s14, 32
	s_mul_i32 s13, s3, s13
	s_mul_hi_u32 s14, s3, s12
	s_add_i32 s13, s14, s13
	s_add_i32 s13, s13, s15
	s_mul_i32 s3, s3, s12
	v_add_u32_e32 v9, s33, v9
	s_add_u32 s12, s35, s3
	v_lshl_add_u64 v[174:175], v[4:5], 0, v[8:9]
	s_addc_u32 s13, s19, s13
	v_mov_b32_e32 v4, 0
	v_lshl_add_u64 v[176:177], s[12:13], 0, v[6:7]
	s_mov_b32 s3, 1
	s_mov_b32 s14, 0
	s_mov_b64 s[12:13], 0
	v_mov_b32_e32 v5, v4
	v_mov_b32_e32 v6, v4
	v_mov_b32_e32 v7, v4
	v_mov_b32_e32 v8, v4
	v_mov_b32_e32 v9, v4
	v_mov_b32_e32 v10, v4
	v_mov_b32_e32 v11, v4
	v_mov_b32_e32 v12, v4
	v_mov_b32_e32 v13, v4
	v_mov_b32_e32 v14, v4
	v_mov_b32_e32 v15, v4
	v_mov_b32_e32 v16, v4
	v_mov_b32_e32 v17, v4
	v_mov_b32_e32 v18, v4
	v_mov_b32_e32 v19, v4
	v_mov_b32_e32 v20, v4
	v_mov_b32_e32 v21, v4
	v_mov_b32_e32 v22, v4
	v_mov_b32_e32 v23, v4
	v_mov_b32_e32 v24, v4
	v_mov_b32_e32 v25, v4
	v_mov_b32_e32 v26, v4
	v_mov_b32_e32 v27, v4
	v_mov_b32_e32 v28, v4
	v_mov_b32_e32 v29, v4
	v_mov_b32_e32 v30, v4
	v_mov_b32_e32 v31, v4
	v_mov_b32_e32 v32, v4
	v_mov_b32_e32 v33, v4
	v_mov_b32_e32 v34, v4
	v_mov_b32_e32 v35, v4
	v_mov_b32_e32 v36, v4
	v_mov_b32_e32 v37, v4
	v_mov_b32_e32 v38, v4
	v_mov_b32_e32 v39, v4
	v_mov_b32_e32 v40, v4
	v_mov_b32_e32 v41, v4
	v_mov_b32_e32 v42, v4
	v_mov_b32_e32 v43, v4
	v_mov_b32_e32 v44, v4
	v_mov_b32_e32 v45, v4
	v_mov_b32_e32 v46, v4
	v_mov_b32_e32 v47, v4
	v_mov_b32_e32 v48, v4
	v_mov_b32_e32 v49, v4
	v_mov_b32_e32 v50, v4
	v_mov_b32_e32 v51, v4
	v_mov_b32_e32 v52, v4
	v_mov_b32_e32 v53, v4
	v_mov_b32_e32 v54, v4
	v_mov_b32_e32 v55, v4
	v_mov_b32_e32 v56, v4
	v_mov_b32_e32 v57, v4
	v_mov_b32_e32 v58, v4
	v_mov_b32_e32 v59, v4
	v_mov_b32_e32 v60, v4
	v_mov_b32_e32 v61, v4
	v_mov_b32_e32 v62, v4
	v_mov_b32_e32 v63, v4
	v_mov_b32_e32 v64, v4
	v_mov_b32_e32 v65, v4
	v_mov_b32_e32 v66, v4
	v_mov_b32_e32 v67, v4
	v_mov_b32_e32 v68, v4
	v_mov_b32_e32 v69, v4
	v_mov_b32_e32 v70, v4
	v_mov_b32_e32 v71, v4
	v_mov_b32_e32 v72, v4
	v_mov_b32_e32 v73, v4
	v_mov_b32_e32 v74, v4
	v_mov_b32_e32 v75, v4
	v_mov_b32_e32 v76, v4
	v_mov_b32_e32 v77, v4
	v_mov_b32_e32 v78, v4
	v_mov_b32_e32 v79, v4
	v_mov_b32_e32 v80, v4
	v_mov_b32_e32 v81, v4
	v_mov_b32_e32 v82, v4
	v_mov_b32_e32 v83, v4
	v_mov_b32_e32 v84, v4
	v_mov_b32_e32 v85, v4
	v_mov_b32_e32 v86, v4
	v_mov_b32_e32 v87, v4
	v_mov_b32_e32 v88, v4
	v_mov_b32_e32 v89, v4
	v_mov_b32_e32 v90, v4
	v_mov_b32_e32 v91, v4
	v_mov_b32_e32 v92, v4
	v_mov_b32_e32 v93, v4
	v_mov_b32_e32 v94, v4
	v_mov_b32_e32 v95, v4
	v_mov_b32_e32 v96, v4
	v_mov_b32_e32 v97, v4
	v_mov_b32_e32 v98, v4
	v_mov_b32_e32 v99, v4
	v_mov_b32_e32 v116, v4
	v_mov_b32_e32 v117, v4
	v_mov_b32_e32 v118, v4
	v_mov_b32_e32 v119, v4
	v_mov_b32_e32 v120, v4
	v_mov_b32_e32 v121, v4
	v_mov_b32_e32 v122, v4
	v_mov_b32_e32 v123, v4
	v_mov_b32_e32 v124, v4
	v_mov_b32_e32 v125, v4
	v_mov_b32_e32 v126, v4
	v_mov_b32_e32 v127, v4
	v_mov_b32_e32 v128, v4
	v_mov_b32_e32 v129, v4
	v_mov_b32_e32 v130, v4
	v_mov_b32_e32 v131, v4
	v_mov_b32_e32 v100, v4
	v_mov_b32_e32 v101, v4
	v_mov_b32_e32 v102, v4
	v_mov_b32_e32 v103, v4
	v_mov_b32_e32 v104, v4
	v_mov_b32_e32 v105, v4
	v_mov_b32_e32 v106, v4
	v_mov_b32_e32 v107, v4
	v_mov_b32_e32 v108, v4
	v_mov_b32_e32 v109, v4
	v_mov_b32_e32 v110, v4
	v_mov_b32_e32 v111, v4
	v_mov_b32_e32 v112, v4
	v_mov_b32_e32 v113, v4
	v_mov_b32_e32 v114, v4
	v_mov_b32_e32 v115, v4
	s_cmp_ge_u32 s41, 0x100
	s_cbranch_scc1 .Lnl_624
	.p2align 6
.LBB0_624:
	s_and_b32 s16, s14, 0x10000
	s_xor_b32 s17, s16, 0x10000
	v_xor_b32_e32 v217, s16, v215
	v_bitop3_b32 v218, v215, s16, 64 bitop3:0x96
	v_bitop3_b32 v220, v216, s16, 64 bitop3:0x96
	v_xor_b32_e32 v219, s17, v216
	v_xor_b32_e32 v221, s17, v215
	s_waitcnt lgkmcnt(2)
	v_mfma_f32_16x16x32_bf16 v[100:103], v[148:151], v[132:135], v[100:103]
	s_add_i32 s15, s14, 0x10000
	s_and_b32 s17, s15, 0x10000
	s_add_i32 s17, s0, s17
	s_lshl_b64 s[98:99], s[10:11], 4
	s_add_u32 s98, s98, s12
	s_addc_u32 s99, s99, s13
	v_lshl_add_u64 v[246:247], v[174:175], 0, s[12:13]
	s_add_i32 m0, s17, 0x800
	v_mfma_f32_16x16x32_bf16 v[104:107], v[148:151], v[136:139], v[104:107]
	v_mfma_f32_16x16x32_bf16 v[116:119], v[148:151], v[140:143], v[116:119]
	global_load_lds_dwordx4 v[246:247], off
	s_add_i32 m0, s17, 0x4800
	v_lshl_add_u64 v[248:249], v[174:175], 0, s[98:99]
	v_mfma_f32_16x16x32_bf16 v[120:123], v[148:151], v[144:147], v[120:123]
	ds_read_b128 v[148:151], v217 offset:8192
	v_mfma_f32_16x16x32_bf16 v[108:111], v[152:155], v[132:135], v[108:111]
	ds_read_b128 v[222:225], v220
	global_load_lds_dwordx4 v[248:249], off
	s_add_i32 m0, s17, 0x8800
	v_lshl_add_u64 v[246:247], v[176:177], 0, s[12:13]
	v_mfma_f32_16x16x32_bf16 v[112:115], v[152:155], v[136:139], v[112:115]
	v_mfma_f32_16x16x32_bf16 v[124:127], v[152:155], v[140:143], v[124:127]
	global_load_lds_dwordx4 v[246:247], off
	s_add_i32 m0, s17, 0xc800
	v_lshl_add_u64 v[248:249], v[176:177], 0, s[98:99]
	v_mfma_f32_16x16x32_bf16 v[128:131], v[152:155], v[144:147], v[128:131]
	ds_read_b128 v[152:155], v217 offset:10240
	s_waitcnt lgkmcnt(3)
	v_mfma_f32_16x16x32_bf16 v[84:87], v[238:241], v[132:135], v[84:87]
	ds_read_b128 v[226:229], v220 offset:2048
	global_load_lds_dwordx4 v[248:249], off
	s_add_i32 m0, s17, 0xc00
	v_lshl_add_u64 v[246:247], v[172:173], 0, s[12:13]
	v_mfma_f32_16x16x32_bf16 v[88:91], v[238:241], v[136:139], v[88:91]
	v_mfma_f32_16x16x32_bf16 v[68:71], v[238:241], v[140:143], v[68:71]
	global_load_lds_dwordx4 v[246:247], off
	s_add_i32 m0, s17, 0x4c00
	v_lshl_add_u64 v[248:249], v[172:173], 0, s[98:99]
	v_mfma_f32_16x16x32_bf16 v[72:75], v[238:241], v[144:147], v[72:75]
	ds_read_b128 v[238:241], v217 offset:12288
	v_mfma_f32_16x16x32_bf16 v[92:95], v[242:245], v[132:135], v[92:95]
	ds_read_b128 v[230:233], v220 offset:4096
	global_load_lds_dwordx4 v[248:249], off
	s_add_i32 m0, s17, 0x8c00
	v_lshl_add_u64 v[246:247], v[170:171], 0, s[12:13]
	v_mfma_f32_16x16x32_bf16 v[96:99], v[242:245], v[136:139], v[96:99]
	v_mfma_f32_16x16x32_bf16 v[76:79], v[242:245], v[140:143], v[76:79]
	global_load_lds_dwordx4 v[246:247], off
	s_add_i32 m0, s17, 0xcc00
	v_lshl_add_u64 v[248:249], v[170:171], 0, s[98:99]
	v_mfma_f32_16x16x32_bf16 v[80:83], v[242:245], v[144:147], v[80:83]
	ds_read_b128 v[242:245], v217 offset:14336
	s_waitcnt lgkmcnt(4)
	v_mfma_f32_16x16x32_bf16 v[52:55], v[148:151], v[132:135], v[52:55]
	ds_read_b128 v[234:237], v220 offset:6144
	global_load_lds_dwordx4 v[248:249], off
	v_mfma_f32_16x16x32_bf16 v[56:59], v[148:151], v[136:139], v[56:59]
	v_mfma_f32_16x16x32_bf16 v[36:39], v[148:151], v[140:143], v[36:39]
	v_mfma_f32_16x16x32_bf16 v[40:43], v[148:151], v[144:147], v[40:43]
	ds_read_b128 v[148:151], v218
	v_mfma_f32_16x16x32_bf16 v[60:63], v[152:155], v[132:135], v[60:63]
	v_mfma_f32_16x16x32_bf16 v[64:67], v[152:155], v[136:139], v[64:67]
	v_mfma_f32_16x16x32_bf16 v[44:47], v[152:155], v[140:143], v[44:47]
	v_mfma_f32_16x16x32_bf16 v[48:51], v[152:155], v[144:147], v[48:51]
	ds_read_b128 v[152:155], v218 offset:2048
	s_waitcnt lgkmcnt(3)
	v_mfma_f32_16x16x32_bf16 v[20:23], v[238:241], v[132:135], v[20:23]
	v_mfma_f32_16x16x32_bf16 v[24:27], v[238:241], v[136:139], v[24:27]
	v_mfma_f32_16x16x32_bf16 v[4:7], v[238:241], v[140:143], v[4:7]
	v_mfma_f32_16x16x32_bf16 v[8:11], v[238:241], v[144:147], v[8:11]
	ds_read_b128 v[238:241], v218 offset:4096
	v_mfma_f32_16x16x32_bf16 v[28:31], v[242:245], v[132:135], v[28:31]
	v_mfma_f32_16x16x32_bf16 v[32:35], v[242:245], v[136:139], v[32:35]
	v_mfma_f32_16x16x32_bf16 v[12:15], v[242:245], v[140:143], v[12:15]
	v_mfma_f32_16x16x32_bf16 v[16:19], v[242:245], v[144:147], v[16:19]
	ds_read_b128 v[242:245], v218 offset:6144
	s_waitcnt lgkmcnt(2)
	v_mfma_f32_16x16x32_bf16 v[100:103], v[148:151], v[222:225], v[100:103]
	v_mfma_f32_16x16x32_bf16 v[104:107], v[148:151], v[226:229], v[104:107]
	v_mfma_f32_16x16x32_bf16 v[116:119], v[148:151], v[230:233], v[116:119]
	v_mfma_f32_16x16x32_bf16 v[120:123], v[148:151], v[234:237], v[120:123]
	ds_read_b128 v[148:151], v218 offset:8192
	v_mfma_f32_16x16x32_bf16 v[108:111], v[152:155], v[222:225], v[108:111]
	v_mfma_f32_16x16x32_bf16 v[112:115], v[152:155], v[226:229], v[112:115]
	v_mfma_f32_16x16x32_bf16 v[124:127], v[152:155], v[230:233], v[124:127]
	v_mfma_f32_16x16x32_bf16 v[128:131], v[152:155], v[234:237], v[128:131]
	ds_read_b128 v[152:155], v218 offset:10240
	s_waitcnt lgkmcnt(2)
	v_mfma_f32_16x16x32_bf16 v[84:87], v[238:241], v[222:225], v[84:87]
	v_mfma_f32_16x16x32_bf16 v[88:91], v[238:241], v[226:229], v[88:91]
	v_mfma_f32_16x16x32_bf16 v[68:71], v[238:241], v[230:233], v[68:71]
	v_mfma_f32_16x16x32_bf16 v[72:75], v[238:241], v[234:237], v[72:75]
	ds_read_b128 v[238:241], v218 offset:12288
	v_mfma_f32_16x16x32_bf16 v[92:95], v[242:245], v[222:225], v[92:95]
	v_mfma_f32_16x16x32_bf16 v[96:99], v[242:245], v[226:229], v[96:99]
	v_mfma_f32_16x16x32_bf16 v[76:79], v[242:245], v[230:233], v[76:79]
	v_mfma_f32_16x16x32_bf16 v[80:83], v[242:245], v[234:237], v[80:83]
	ds_read_b128 v[242:245], v218 offset:14336
	s_waitcnt lgkmcnt(2)
	v_mfma_f32_16x16x32_bf16 v[52:55], v[148:151], v[222:225], v[52:55]
	v_mfma_f32_16x16x32_bf16 v[56:59], v[148:151], v[226:229], v[56:59]
	v_mfma_f32_16x16x32_bf16 v[36:39], v[148:151], v[230:233], v[36:39]
	v_mfma_f32_16x16x32_bf16 v[40:43], v[148:151], v[234:237], v[40:43]
	s_add_i32 s3, s3, 1
	s_min_i32 s38, s3, s1
	s_ashr_i32 s39, s38, 31
	s_lshl_b64 s[38:39], s[38:39], 7
	s_add_i32 s14, s0, s16
	s_add_u32 s16, s38, s10
	s_addc_u32 s17, s39, s11
	s_lshl_b64 s[98:99], s[10:11], 4
	s_add_u32 s98, s98, s38
	s_addc_u32 s99, s99, s39
	v_lshl_add_u64 v[246:247], v[162:163], 0, s[38:39]
	s_mov_b32 m0, s14
	s_waitcnt vmcnt(0) lgkmcnt(0)
	s_barrier
	ds_read_b128 v[132:135], v219
	ds_read_b128 v[136:139], v219 offset:2048
	v_mfma_f32_16x16x32_bf16 v[60:63], v[152:155], v[222:225], v[60:63]
	global_load_lds_dwordx4 v[246:247], off
	s_add_i32 m0, s14, 0x4000
	v_lshl_add_u64 v[248:249], v[162:163], 0, s[98:99]
	ds_read_b128 v[140:143], v219 offset:4096
	ds_read_b128 v[144:147], v219 offset:6144
	v_mfma_f32_16x16x32_bf16 v[64:67], v[152:155], v[226:229], v[64:67]
	global_load_lds_dwordx4 v[248:249], off
	s_add_i32 m0, s14, 0x8000
	v_lshl_add_u64 v[246:247], v[164:165], 0, s[38:39]
	ds_read_b128 v[148:151], v221
	v_mfma_f32_16x16x32_bf16 v[44:47], v[152:155], v[230:233], v[44:47]
	global_load_lds_dwordx4 v[246:247], off
	s_add_i32 m0, s14, 0xc000
	v_lshl_add_u64 v[248:249], v[164:165], 0, s[98:99]
	v_mfma_f32_16x16x32_bf16 v[48:51], v[152:155], v[234:237], v[48:51]
	global_load_lds_dwordx4 v[248:249], off
	s_add_i32 m0, s14, 0x400
	v_lshl_add_u64 v[246:247], v[166:167], 0, s[16:17]
	ds_read_b128 v[152:155], v221 offset:2048
	v_mfma_f32_16x16x32_bf16 v[20:23], v[238:241], v[222:225], v[20:23]
	global_load_lds_dwordx4 v[246:247], off
	s_add_i32 m0, s14, 0x8400
	v_lshl_add_u64 v[248:249], v[168:169], 0, s[16:17]
	v_mfma_f32_16x16x32_bf16 v[24:27], v[238:241], v[226:229], v[24:27]
	global_load_lds_dwordx4 v[248:249], off
	s_add_u32 s98, s98, s10
	s_addc_u32 s99, s99, s11
	v_lshl_add_u64 v[246:247], v[166:167], 0, s[98:99]
	s_add_i32 m0, s14, 0x4400
	v_mfma_f32_16x16x32_bf16 v[4:7], v[238:241], v[230:233], v[4:7]
	global_load_lds_dwordx4 v[246:247], off
	s_add_i32 m0, s14, 0xc400
	v_lshl_add_u64 v[248:249], v[168:169], 0, s[98:99]
	v_mfma_f32_16x16x32_bf16 v[8:11], v[238:241], v[234:237], v[8:11]
	global_load_lds_dwordx4 v[248:249], off
	ds_read_b128 v[238:241], v221 offset:4096
	v_mfma_f32_16x16x32_bf16 v[28:31], v[242:245], v[222:225], v[28:31]
	v_mfma_f32_16x16x32_bf16 v[32:35], v[242:245], v[226:229], v[32:35]
	v_mfma_f32_16x16x32_bf16 v[12:15], v[242:245], v[230:233], v[12:15]
	v_mfma_f32_16x16x32_bf16 v[16:19], v[242:245], v[234:237], v[16:19]
	ds_read_b128 v[242:245], v221 offset:6144
	s_add_u32 s12, s12, 0x80
	s_addc_u32 s13, s13, 0
	s_cmp_eq_u32 s5, s3
	s_mov_b32 s14, s15
	s_cbranch_scc0 .LBB0_624
	s_branch .LBB0_626
.Lnl_624:
	s_and_b32 s16, s14, 0x10000
	s_xor_b32 s17, s16, 0x10000
	v_xor_b32_e32 v217, s16, v215
	v_bitop3_b32 v218, v215, s16, 64 bitop3:0x96
	v_bitop3_b32 v220, v216, s16, 64 bitop3:0x96
	v_xor_b32_e32 v219, s17, v216
	v_xor_b32_e32 v221, s17, v215
	s_waitcnt lgkmcnt(2)
	v_mfma_f32_16x16x32_bf16 v[100:103], v[148:151], v[132:135], v[100:103]
	s_add_i32 s15, s14, 0x10000
	v_mfma_f32_16x16x32_bf16 v[104:107], v[148:151], v[136:139], v[104:107]
	v_mfma_f32_16x16x32_bf16 v[116:119], v[148:151], v[140:143], v[116:119]
	v_mfma_f32_16x16x32_bf16 v[120:123], v[148:151], v[144:147], v[120:123]
	ds_read_b128 v[148:151], v217 offset:8192
	v_mfma_f32_16x16x32_bf16 v[108:111], v[152:155], v[132:135], v[108:111]
	ds_read_b128 v[222:225], v220
	v_mfma_f32_16x16x32_bf16 v[112:115], v[152:155], v[136:139], v[112:115]
	v_mfma_f32_16x16x32_bf16 v[124:127], v[152:155], v[140:143], v[124:127]
	v_mfma_f32_16x16x32_bf16 v[128:131], v[152:155], v[144:147], v[128:131]
	ds_read_b128 v[152:155], v217 offset:10240
	s_waitcnt lgkmcnt(3)
	v_mfma_f32_16x16x32_bf16 v[84:87], v[238:241], v[132:135], v[84:87]
	ds_read_b128 v[226:229], v220 offset:2048
	v_mfma_f32_16x16x32_bf16 v[88:91], v[238:241], v[136:139], v[88:91]
	v_mfma_f32_16x16x32_bf16 v[68:71], v[238:241], v[140:143], v[68:71]
	v_mfma_f32_16x16x32_bf16 v[72:75], v[238:241], v[144:147], v[72:75]
	ds_read_b128 v[238:241], v217 offset:12288
	v_mfma_f32_16x16x32_bf16 v[92:95], v[242:245], v[132:135], v[92:95]
	ds_read_b128 v[230:233], v220 offset:4096
	v_mfma_f32_16x16x32_bf16 v[96:99], v[242:245], v[136:139], v[96:99]
	v_mfma_f32_16x16x32_bf16 v[76:79], v[242:245], v[140:143], v[76:79]
	v_mfma_f32_16x16x32_bf16 v[80:83], v[242:245], v[144:147], v[80:83]
	ds_read_b128 v[242:245], v217 offset:14336
	s_waitcnt lgkmcnt(4)
	v_mfma_f32_16x16x32_bf16 v[52:55], v[148:151], v[132:135], v[52:55]
	ds_read_b128 v[234:237], v220 offset:6144
	v_mfma_f32_16x16x32_bf16 v[56:59], v[148:151], v[136:139], v[56:59]
	v_mfma_f32_16x16x32_bf16 v[36:39], v[148:151], v[140:143], v[36:39]
	v_mfma_f32_16x16x32_bf16 v[40:43], v[148:151], v[144:147], v[40:43]
	ds_read_b128 v[148:151], v218
	v_mfma_f32_16x16x32_bf16 v[60:63], v[152:155], v[132:135], v[60:63]
	v_mfma_f32_16x16x32_bf16 v[64:67], v[152:155], v[136:139], v[64:67]
	v_mfma_f32_16x16x32_bf16 v[44:47], v[152:155], v[140:143], v[44:47]
	v_mfma_f32_16x16x32_bf16 v[48:51], v[152:155], v[144:147], v[48:51]
	ds_read_b128 v[152:155], v218 offset:2048
	s_waitcnt lgkmcnt(3)
	v_mfma_f32_16x16x32_bf16 v[20:23], v[238:241], v[132:135], v[20:23]
	v_mfma_f32_16x16x32_bf16 v[24:27], v[238:241], v[136:139], v[24:27]
	v_mfma_f32_16x16x32_bf16 v[4:7], v[238:241], v[140:143], v[4:7]
	v_mfma_f32_16x16x32_bf16 v[8:11], v[238:241], v[144:147], v[8:11]
	ds_read_b128 v[238:241], v218 offset:4096
	v_mfma_f32_16x16x32_bf16 v[28:31], v[242:245], v[132:135], v[28:31]
	v_mfma_f32_16x16x32_bf16 v[32:35], v[242:245], v[136:139], v[32:35]
	v_mfma_f32_16x16x32_bf16 v[12:15], v[242:245], v[140:143], v[12:15]
	v_mfma_f32_16x16x32_bf16 v[16:19], v[242:245], v[144:147], v[16:19]
	ds_read_b128 v[242:245], v218 offset:6144
	s_waitcnt lgkmcnt(2)
	v_mfma_f32_16x16x32_bf16 v[100:103], v[148:151], v[222:225], v[100:103]
	v_mfma_f32_16x16x32_bf16 v[104:107], v[148:151], v[226:229], v[104:107]
	v_mfma_f32_16x16x32_bf16 v[116:119], v[148:151], v[230:233], v[116:119]
	v_mfma_f32_16x16x32_bf16 v[120:123], v[148:151], v[234:237], v[120:123]
	ds_read_b128 v[148:151], v218 offset:8192
	v_mfma_f32_16x16x32_bf16 v[108:111], v[152:155], v[222:225], v[108:111]
	v_mfma_f32_16x16x32_bf16 v[112:115], v[152:155], v[226:229], v[112:115]
	v_mfma_f32_16x16x32_bf16 v[124:127], v[152:155], v[230:233], v[124:127]
	v_mfma_f32_16x16x32_bf16 v[128:131], v[152:155], v[234:237], v[128:131]
	ds_read_b128 v[152:155], v218 offset:10240
	s_waitcnt lgkmcnt(2)
	v_mfma_f32_16x16x32_bf16 v[84:87], v[238:241], v[222:225], v[84:87]
	v_mfma_f32_16x16x32_bf16 v[88:91], v[238:241], v[226:229], v[88:91]
	v_mfma_f32_16x16x32_bf16 v[68:71], v[238:241], v[230:233], v[68:71]
	v_mfma_f32_16x16x32_bf16 v[72:75], v[238:241], v[234:237], v[72:75]
	ds_read_b128 v[238:241], v218 offset:12288
	v_mfma_f32_16x16x32_bf16 v[92:95], v[242:245], v[222:225], v[92:95]
	v_mfma_f32_16x16x32_bf16 v[96:99], v[242:245], v[226:229], v[96:99]
	v_mfma_f32_16x16x32_bf16 v[76:79], v[242:245], v[230:233], v[76:79]
	v_mfma_f32_16x16x32_bf16 v[80:83], v[242:245], v[234:237], v[80:83]
	ds_read_b128 v[242:245], v218 offset:14336
	s_waitcnt lgkmcnt(2)
	v_mfma_f32_16x16x32_bf16 v[52:55], v[148:151], v[222:225], v[52:55]
	v_mfma_f32_16x16x32_bf16 v[56:59], v[148:151], v[226:229], v[56:59]
	v_mfma_f32_16x16x32_bf16 v[36:39], v[148:151], v[230:233], v[36:39]
	v_mfma_f32_16x16x32_bf16 v[40:43], v[148:151], v[234:237], v[40:43]
	s_add_i32 s3, s3, 1
	s_waitcnt vmcnt(0) lgkmcnt(0)
	s_barrier
	ds_read_b128 v[132:135], v219
	ds_read_b128 v[136:139], v219 offset:2048
	v_mfma_f32_16x16x32_bf16 v[60:63], v[152:155], v[222:225], v[60:63]
	ds_read_b128 v[140:143], v219 offset:4096
	ds_read_b128 v[144:147], v219 offset:6144
	v_mfma_f32_16x16x32_bf16 v[64:67], v[152:155], v[226:229], v[64:67]
	ds_read_b128 v[148:151], v221
	v_mfma_f32_16x16x32_bf16 v[44:47], v[152:155], v[230:233], v[44:47]
	v_mfma_f32_16x16x32_bf16 v[48:51], v[152:155], v[234:237], v[48:51]
	ds_read_b128 v[152:155], v221 offset:2048
	v_mfma_f32_16x16x32_bf16 v[20:23], v[238:241], v[222:225], v[20:23]
	v_mfma_f32_16x16x32_bf16 v[24:27], v[238:241], v[226:229], v[24:27]
	v_mfma_f32_16x16x32_bf16 v[4:7], v[238:241], v[230:233], v[4:7]
	v_mfma_f32_16x16x32_bf16 v[8:11], v[238:241], v[234:237], v[8:11]
	ds_read_b128 v[238:241], v221 offset:4096
	v_mfma_f32_16x16x32_bf16 v[28:31], v[242:245], v[222:225], v[28:31]
	v_mfma_f32_16x16x32_bf16 v[32:35], v[242:245], v[226:229], v[32:35]
	v_mfma_f32_16x16x32_bf16 v[12:15], v[242:245], v[230:233], v[12:15]
	v_mfma_f32_16x16x32_bf16 v[16:19], v[242:245], v[234:237], v[16:19]
	ds_read_b128 v[242:245], v221 offset:6144
	s_add_u32 s12, s12, 0x80
	s_addc_u32 s13, s13, 0
	s_cmp_eq_u32 s5, s3
	s_mov_b32 s14, s15
	s_cbranch_scc0 .Lnl_624
	s_branch .LBB0_626
